# residual epilogue of w_out/ffn_down GEMMs rewritten: 12 loads in flight instead of 32 serialized load-wait-store round trips (same fma per element)
# speedup vs baseline: 1.1767x; 1.0313x over previous
.LBB0_1032:
	v_add_u32_e32 v0, s85, v217
	ds_read_b128 v[130:133], v0
	ds_read_b128 v[150:153], v0 offset:1024
	ds_read_b128 v[154:157], v0 offset:2048
	ds_read_b128 v[158:161], v0 offset:3072
	s_add_i32 s40, s20, 2
	s_add_u32 s24, s0, 0x80
	s_addc_u32 s21, s1, 0
	s_cmp_eq_u32 s73, s20
	s_cselect_b32 s20, s64, s24
	s_cselect_b32 s21, s65, s21
	s_cselect_b32 s25, s67, s39
	s_cselect_b32 s24, s66, s38
	v_lshl_add_u64 v[194:195], s[0:1], 0, v[146:147]
	s_add_i32 m0, s60, 0xc000
	ds_read_b128 v[162:165], v220
	ds_read_b128 v[166:169], v220 offset:1024
	ds_read_b128 v[170:173], v220 offset:2048
	ds_read_b128 v[174:177], v220 offset:3072
	ds_read_b128 v[178:181], v220 offset:4096
	ds_read_b128 v[182:185], v220 offset:5120
	ds_read_b128 v[186:189], v220 offset:6144
	ds_read_b128 v[190:193], v220 offset:7168
	global_load_lds_dwordx4 v[194:195], off
	v_lshl_add_u64 v[194:195], s[0:1], 0, v[148:149]
	s_add_i32 m0, s60, 0xe000
	s_nop 0
	global_load_lds_dwordx4 v[194:195], off
	s_waitcnt lgkmcnt(8)
	s_barrier
	s_waitcnt lgkmcnt(0)
	s_setprio 1
	s_waitcnt lgkmcnt(0)
	v_mfma_f32_16x16x32_bf16 v[126:129], v[130:133], v[162:165], v[126:129]
	v_mfma_f32_16x16x32_bf16 v[122:125], v[154:157], v[162:165], v[122:125]
	v_mfma_f32_16x16x32_bf16 v[118:121], v[130:133], v[170:173], v[118:121]
	v_mfma_f32_16x16x32_bf16 v[114:117], v[154:157], v[170:173], v[114:117]
	v_mfma_f32_16x16x32_bf16 v[110:113], v[130:133], v[178:181], v[110:113]
	v_mfma_f32_16x16x32_bf16 v[106:109], v[154:157], v[178:181], v[106:109]
	v_mfma_f32_16x16x32_bf16 v[102:105], v[130:133], v[186:189], v[102:105]
	v_mfma_f32_16x16x32_bf16 v[98:101], v[154:157], v[186:189], v[98:101]
	v_mfma_f32_16x16x32_bf16 v[126:129], v[150:153], v[166:169], v[126:129]
	v_mfma_f32_16x16x32_bf16 v[122:125], v[158:161], v[166:169], v[122:125]
	v_mfma_f32_16x16x32_bf16 v[118:121], v[150:153], v[174:177], v[118:121]
	v_mfma_f32_16x16x32_bf16 v[114:117], v[158:161], v[174:177], v[114:117]
	v_mfma_f32_16x16x32_bf16 v[110:113], v[150:153], v[182:185], v[110:113]
	v_mfma_f32_16x16x32_bf16 v[106:109], v[158:161], v[182:185], v[106:109]
	v_mfma_f32_16x16x32_bf16 v[102:105], v[150:153], v[190:193], v[102:105]
	v_mfma_f32_16x16x32_bf16 v[98:101], v[158:161], v[190:193], v[98:101]
	s_setprio 0
	s_barrier
	s_add_i32 s41, s85, s63
	v_add_u32_e32 v0, s96, v217
	v_lshl_add_u64 v[236:237], s[24:25], 0, v[138:139]
	s_mov_b32 m0, s41
	ds_read_b128 v[194:197], v0
	ds_read_b128 v[224:227], v0 offset:1024
	ds_read_b128 v[228:231], v0 offset:2048
	ds_read_b128 v[232:235], v0 offset:3072
	global_load_lds_dwordx4 v[236:237], off
	v_lshl_add_u64 v[238:239], s[24:25], 0, v[140:141]
	s_add_i32 m0, s41, 0x2000
	s_nop 0
	global_load_lds_dwordx4 v[238:239], off
	s_barrier
	s_waitcnt lgkmcnt(0)
	s_setprio 1
	s_waitcnt lgkmcnt(0)
	v_mfma_f32_16x16x32_bf16 v[62:65], v[194:197], v[162:165], v[62:65]
	v_mfma_f32_16x16x32_bf16 v[58:61], v[228:231], v[162:165], v[58:61]
	v_mfma_f32_16x16x32_bf16 v[54:57], v[194:197], v[170:173], v[54:57]
	v_mfma_f32_16x16x32_bf16 v[50:53], v[228:231], v[170:173], v[50:53]
	v_mfma_f32_16x16x32_bf16 v[46:49], v[194:197], v[178:181], v[46:49]
	v_mfma_f32_16x16x32_bf16 v[42:45], v[228:231], v[178:181], v[42:45]
	v_mfma_f32_16x16x32_bf16 v[38:41], v[194:197], v[186:189], v[38:41]
	v_mfma_f32_16x16x32_bf16 v[34:37], v[228:231], v[186:189], v[34:37]
	v_mfma_f32_16x16x32_bf16 v[62:65], v[224:227], v[166:169], v[62:65]
	v_mfma_f32_16x16x32_bf16 v[58:61], v[232:235], v[166:169], v[58:61]
	v_mfma_f32_16x16x32_bf16 v[54:57], v[224:227], v[174:177], v[54:57]
	v_mfma_f32_16x16x32_bf16 v[50:53], v[232:235], v[174:177], v[50:53]
	v_mfma_f32_16x16x32_bf16 v[46:49], v[224:227], v[182:185], v[46:49]
	v_mfma_f32_16x16x32_bf16 v[42:45], v[232:235], v[182:185], v[42:45]
	v_mfma_f32_16x16x32_bf16 v[38:41], v[224:227], v[190:193], v[38:41]
	v_mfma_f32_16x16x32_bf16 v[34:37], v[232:235], v[190:193], v[34:37]
	s_setprio 0
	s_mov_b32 m0, s60
	v_lshl_add_u64 v[240:241], s[20:21], 0, v[138:139]
	s_barrier
	ds_read_b128 v[162:165], v220 offset:16384
	ds_read_b128 v[166:169], v220 offset:17408
	ds_read_b128 v[170:173], v220 offset:18432
	ds_read_b128 v[174:177], v220 offset:19456
	ds_read_b128 v[178:181], v220 offset:20480
	ds_read_b128 v[182:185], v220 offset:21504
	ds_read_b128 v[186:189], v220 offset:22528
	ds_read_b128 v[190:193], v220 offset:23552
	global_load_lds_dwordx4 v[240:241], off
	v_lshl_add_u64 v[242:243], s[20:21], 0, v[140:141]
	s_mov_b32 m0, s61
	s_nop 0
	global_load_lds_dwordx4 v[242:243], off
	s_barrier
	s_waitcnt lgkmcnt(0)
	s_setprio 1
	s_waitcnt lgkmcnt(0)
	v_mfma_f32_16x16x32_bf16 v[94:97], v[130:133], v[162:165], v[94:97]
	v_mfma_f32_16x16x32_bf16 v[90:93], v[154:157], v[162:165], v[90:93]
	v_mfma_f32_16x16x32_bf16 v[86:89], v[130:133], v[170:173], v[86:89]
	v_mfma_f32_16x16x32_bf16 v[82:85], v[154:157], v[170:173], v[82:85]
	v_mfma_f32_16x16x32_bf16 v[78:81], v[130:133], v[178:181], v[78:81]
	v_mfma_f32_16x16x32_bf16 v[74:77], v[154:157], v[178:181], v[74:77]
	v_mfma_f32_16x16x32_bf16 v[70:73], v[130:133], v[186:189], v[70:73]
	v_mfma_f32_16x16x32_bf16 v[66:69], v[154:157], v[186:189], v[66:69]
	v_mfma_f32_16x16x32_bf16 v[94:97], v[150:153], v[166:169], v[94:97]
	v_mfma_f32_16x16x32_bf16 v[90:93], v[158:161], v[166:169], v[90:93]
	v_mfma_f32_16x16x32_bf16 v[86:89], v[150:153], v[174:177], v[86:89]
	v_mfma_f32_16x16x32_bf16 v[82:85], v[158:161], v[174:177], v[82:85]
	v_mfma_f32_16x16x32_bf16 v[78:81], v[150:153], v[182:185], v[78:81]
	v_mfma_f32_16x16x32_bf16 v[74:77], v[158:161], v[182:185], v[74:77]
	v_mfma_f32_16x16x32_bf16 v[70:73], v[150:153], v[190:193], v[70:73]
	v_mfma_f32_16x16x32_bf16 v[66:69], v[158:161], v[190:193], v[66:69]
	s_setprio 0
	s_barrier
	s_add_u32 s24, s24, s74
	s_addc_u32 s25, s25, 0
	s_add_i32 s41, s96, s63
	v_lshl_add_u64 v[244:245], s[24:25], 0, v[138:139]
	s_mov_b32 m0, s41
	v_lshl_add_u64 v[246:247], s[24:25], 0, v[140:141]
	global_load_lds_dwordx4 v[244:245], off
	s_add_i32 m0, s41, 0x2000
	s_nop 0
	global_load_lds_dwordx4 v[246:247], off
	s_waitcnt vmcnt(6)
	s_barrier
	s_setprio 1
	v_mfma_f32_16x16x32_bf16 v[30:33], v[194:197], v[162:165], v[30:33]
	v_mfma_f32_16x16x32_bf16 v[26:29], v[228:231], v[162:165], v[26:29]
	v_mfma_f32_16x16x32_bf16 v[22:25], v[194:197], v[170:173], v[22:25]
	v_mfma_f32_16x16x32_bf16 v[18:21], v[228:231], v[170:173], v[18:21]
	v_mfma_f32_16x16x32_bf16 v[14:17], v[194:197], v[178:181], v[14:17]
	v_mfma_f32_16x16x32_bf16 v[10:13], v[228:231], v[178:181], v[10:13]
	v_mfma_f32_16x16x32_bf16 v[6:9], v[194:197], v[186:189], v[6:9]
	v_mfma_f32_16x16x32_bf16 v[2:5], v[228:231], v[186:189], v[2:5]
	v_mfma_f32_16x16x32_bf16 v[30:33], v[224:227], v[166:169], v[30:33]
	v_mfma_f32_16x16x32_bf16 v[26:29], v[232:235], v[166:169], v[26:29]
	v_mfma_f32_16x16x32_bf16 v[22:25], v[224:227], v[174:177], v[22:25]
	v_mfma_f32_16x16x32_bf16 v[18:21], v[232:235], v[174:177], v[18:21]
	v_mfma_f32_16x16x32_bf16 v[14:17], v[224:227], v[182:185], v[14:17]
	v_mfma_f32_16x16x32_bf16 v[10:13], v[232:235], v[182:185], v[10:13]
	v_mfma_f32_16x16x32_bf16 v[6:9], v[224:227], v[190:193], v[6:9]
	v_mfma_f32_16x16x32_bf16 v[2:5], v[232:235], v[190:193], v[2:5]
	s_setprio 0
	s_mov_b32 s24, 0x18000
	s_addk_i32 s24, 0x50
	v_add_u32_e32 v0, s24, v217
	s_barrier
	ds_read_b128 v[130:133], v0
	ds_read_b128 v[150:153], v0 offset:1024
	ds_read_b128 v[154:157], v0 offset:2048
	ds_read_b128 v[158:161], v0 offset:3072
	s_add_u32 s20, s20, s74
	s_addc_u32 s21, s21, 0
	s_mov_b32 m0, s58
	v_lshl_add_u64 v[194:195], s[20:21], 0, v[138:139]
	ds_read_b128 v[162:165], v220 offset:32768
	ds_read_b128 v[166:169], v220 offset:33792
	ds_read_b128 v[170:173], v220 offset:34816
	ds_read_b128 v[174:177], v220 offset:35840
	ds_read_b128 v[178:181], v220 offset:36864
	ds_read_b128 v[182:185], v220 offset:37888
	ds_read_b128 v[186:189], v220 offset:38912
	ds_read_b128 v[190:193], v220 offset:39936
	global_load_lds_dwordx4 v[194:195], off
	v_lshl_add_u64 v[194:195], s[20:21], 0, v[140:141]
	s_mov_b32 m0, s59
	s_nop 0
	global_load_lds_dwordx4 v[194:195], off
	s_waitcnt lgkmcnt(8)
	s_barrier
	s_waitcnt lgkmcnt(0)
	s_setprio 1
	s_waitcnt lgkmcnt(0)
	v_mfma_f32_16x16x32_bf16 v[126:129], v[130:133], v[162:165], v[126:129]
	v_mfma_f32_16x16x32_bf16 v[122:125], v[154:157], v[162:165], v[122:125]
	v_mfma_f32_16x16x32_bf16 v[118:121], v[130:133], v[170:173], v[118:121]
	v_mfma_f32_16x16x32_bf16 v[114:117], v[154:157], v[170:173], v[114:117]
	v_mfma_f32_16x16x32_bf16 v[110:113], v[130:133], v[178:181], v[110:113]
	v_mfma_f32_16x16x32_bf16 v[106:109], v[154:157], v[178:181], v[106:109]
	v_mfma_f32_16x16x32_bf16 v[102:105], v[130:133], v[186:189], v[102:105]
	v_mfma_f32_16x16x32_bf16 v[98:101], v[154:157], v[186:189], v[98:101]
	v_mfma_f32_16x16x32_bf16 v[126:129], v[150:153], v[166:169], v[126:129]
	v_mfma_f32_16x16x32_bf16 v[122:125], v[158:161], v[166:169], v[122:125]
	v_mfma_f32_16x16x32_bf16 v[118:121], v[150:153], v[174:177], v[118:121]
	v_mfma_f32_16x16x32_bf16 v[114:117], v[158:161], v[174:177], v[114:117]
	v_mfma_f32_16x16x32_bf16 v[110:113], v[150:153], v[182:185], v[110:113]
	v_mfma_f32_16x16x32_bf16 v[106:109], v[158:161], v[182:185], v[106:109]
	v_mfma_f32_16x16x32_bf16 v[102:105], v[150:153], v[190:193], v[102:105]
	v_mfma_f32_16x16x32_bf16 v[98:101], v[158:161], v[190:193], v[98:101]
	s_setprio 0
	s_barrier
	s_add_i32 s20, s24, s63
	v_add_u32_e32 v0, s97, v217
	v_lshl_add_u64 v[236:237], v[236:237], 0, s[82:83]
	s_mov_b32 m0, s20
	ds_read_b128 v[194:197], v0
	ds_read_b128 v[224:227], v0 offset:1024
	ds_read_b128 v[228:231], v0 offset:2048
	ds_read_b128 v[232:235], v0 offset:3072
	global_load_lds_dwordx4 v[236:237], off
	v_lshl_add_u64 v[236:237], v[238:239], 0, s[82:83]
	s_add_i32 m0, s20, 0x2000
	s_nop 0
	global_load_lds_dwordx4 v[236:237], off
	s_barrier
	s_waitcnt lgkmcnt(0)
	s_setprio 1
	s_waitcnt lgkmcnt(0)
	v_mfma_f32_16x16x32_bf16 v[62:65], v[194:197], v[162:165], v[62:65]
	v_mfma_f32_16x16x32_bf16 v[58:61], v[228:231], v[162:165], v[58:61]
	v_mfma_f32_16x16x32_bf16 v[54:57], v[194:197], v[170:173], v[54:57]
	v_mfma_f32_16x16x32_bf16 v[50:53], v[228:231], v[170:173], v[50:53]
	v_mfma_f32_16x16x32_bf16 v[46:49], v[194:197], v[178:181], v[46:49]
	v_mfma_f32_16x16x32_bf16 v[42:45], v[228:231], v[178:181], v[42:45]
	v_mfma_f32_16x16x32_bf16 v[38:41], v[194:197], v[186:189], v[38:41]
	v_mfma_f32_16x16x32_bf16 v[34:37], v[228:231], v[186:189], v[34:37]
	v_mfma_f32_16x16x32_bf16 v[62:65], v[224:227], v[166:169], v[62:65]
	v_mfma_f32_16x16x32_bf16 v[58:61], v[232:235], v[166:169], v[58:61]
	v_mfma_f32_16x16x32_bf16 v[54:57], v[224:227], v[174:177], v[54:57]
	v_mfma_f32_16x16x32_bf16 v[50:53], v[232:235], v[174:177], v[50:53]
	v_mfma_f32_16x16x32_bf16 v[46:49], v[224:227], v[182:185], v[46:49]
	v_mfma_f32_16x16x32_bf16 v[42:45], v[232:235], v[182:185], v[42:45]
	v_mfma_f32_16x16x32_bf16 v[38:41], v[224:227], v[190:193], v[38:41]
	v_mfma_f32_16x16x32_bf16 v[34:37], v[232:235], v[190:193], v[34:37]
	s_setprio 0
	s_mov_b32 m0, s78
	v_lshl_add_u64 v[236:237], v[240:241], 0, s[82:83]
	s_barrier
	ds_read_b128 v[162:165], v220 offset:49152
	ds_read_b128 v[166:169], v220 offset:50176
	ds_read_b128 v[170:173], v220 offset:51200
	ds_read_b128 v[174:177], v220 offset:52224
	ds_read_b128 v[178:181], v220 offset:53248
	ds_read_b128 v[182:185], v220 offset:54272
	ds_read_b128 v[186:189], v220 offset:55296
	ds_read_b128 v[190:193], v220 offset:56320
	global_load_lds_dwordx4 v[236:237], off
	v_lshl_add_u64 v[236:237], v[242:243], 0, s[82:83]
	s_mov_b32 m0, s23
	s_nop 0
	global_load_lds_dwordx4 v[236:237], off
	s_barrier
	s_waitcnt lgkmcnt(0)
	s_setprio 1
	s_waitcnt lgkmcnt(0)
	v_mfma_f32_16x16x32_bf16 v[94:97], v[130:133], v[162:165], v[94:97]
	v_mfma_f32_16x16x32_bf16 v[90:93], v[154:157], v[162:165], v[90:93]
	v_mfma_f32_16x16x32_bf16 v[86:89], v[130:133], v[170:173], v[86:89]
	v_mfma_f32_16x16x32_bf16 v[82:85], v[154:157], v[170:173], v[82:85]
	v_mfma_f32_16x16x32_bf16 v[78:81], v[130:133], v[178:181], v[78:81]
	v_mfma_f32_16x16x32_bf16 v[74:77], v[154:157], v[178:181], v[74:77]
	v_mfma_f32_16x16x32_bf16 v[70:73], v[130:133], v[186:189], v[70:73]
	v_mfma_f32_16x16x32_bf16 v[66:69], v[154:157], v[186:189], v[66:69]
	v_mfma_f32_16x16x32_bf16 v[94:97], v[150:153], v[166:169], v[94:97]
	v_mfma_f32_16x16x32_bf16 v[90:93], v[158:161], v[166:169], v[90:93]
	v_mfma_f32_16x16x32_bf16 v[86:89], v[150:153], v[174:177], v[86:89]
	v_mfma_f32_16x16x32_bf16 v[82:85], v[158:161], v[174:177], v[82:85]
	v_mfma_f32_16x16x32_bf16 v[78:81], v[150:153], v[182:185], v[78:81]
	v_mfma_f32_16x16x32_bf16 v[74:77], v[158:161], v[182:185], v[74:77]
	v_mfma_f32_16x16x32_bf16 v[70:73], v[150:153], v[190:193], v[70:73]
	v_mfma_f32_16x16x32_bf16 v[66:69], v[158:161], v[190:193], v[66:69]
	s_setprio 0
	s_barrier
	s_add_i32 s20, s97, s63
	v_lshl_add_u64 v[130:131], v[244:245], 0, s[82:83]
	s_mov_b32 m0, s20
	s_nop 0
	global_load_lds_dwordx4 v[130:131], off
	v_lshl_add_u64 v[130:131], v[246:247], 0, s[82:83]
	s_add_i32 m0, s20, 0x2000
	s_nop 0
	global_load_lds_dwordx4 v[130:131], off
	s_waitcnt vmcnt(6)
	s_barrier
	s_setprio 1
	v_mfma_f32_16x16x32_bf16 v[30:33], v[194:197], v[162:165], v[30:33]
	v_mfma_f32_16x16x32_bf16 v[26:29], v[228:231], v[162:165], v[26:29]
	v_mfma_f32_16x16x32_bf16 v[22:25], v[194:197], v[170:173], v[22:25]
	v_mfma_f32_16x16x32_bf16 v[18:21], v[228:231], v[170:173], v[18:21]
	v_mfma_f32_16x16x32_bf16 v[14:17], v[194:197], v[178:181], v[14:17]
	v_mfma_f32_16x16x32_bf16 v[10:13], v[228:231], v[178:181], v[10:13]
	v_mfma_f32_16x16x32_bf16 v[6:9], v[194:197], v[186:189], v[6:9]
	v_mfma_f32_16x16x32_bf16 v[2:5], v[228:231], v[186:189], v[2:5]
	v_mfma_f32_16x16x32_bf16 v[30:33], v[224:227], v[166:169], v[30:33]
	v_mfma_f32_16x16x32_bf16 v[26:29], v[232:235], v[166:169], v[26:29]
	v_mfma_f32_16x16x32_bf16 v[22:25], v[224:227], v[174:177], v[22:25]
	v_mfma_f32_16x16x32_bf16 v[18:21], v[232:235], v[174:177], v[18:21]
	v_mfma_f32_16x16x32_bf16 v[14:17], v[224:227], v[182:185], v[14:17]
	v_mfma_f32_16x16x32_bf16 v[10:13], v[232:235], v[182:185], v[10:13]
	v_mfma_f32_16x16x32_bf16 v[6:9], v[224:227], v[190:193], v[6:9]
	v_mfma_f32_16x16x32_bf16 v[2:5], v[232:235], v[190:193], v[2:5]
	s_setprio 0
	s_add_u32 s0, s0, 0x100
	s_addc_u32 s1, s1, 0
	s_add_u32 s38, s38, 0x100
	s_addc_u32 s39, s39, 0
	s_cmp_ge_u32 s40, s34
	s_mov_b32 s20, s40
	s_barrier
	s_cbranch_scc0 .LBB0_1032
	s_lshl_b32 s24, s26, 8
	s_cmp_lt_i32 s56, 1
	s_mov_b64 s[0:1], -1
	s_cbranch_scc1 .LBB0_1279
	s_cmp_lg_u32 s56, 1
	s_cbranch_scc0 .LBB0_1276
	s_add_i32 s0, s24, 0xfffff000
	s_lshr_b32 s0, s0, 12
	s_add_i32 s0, s0, 1
	s_cmp_gt_i32 s26, 15
	v_readlane_b32 s4, v249, 47
	s_cselect_b32 s0, s0, 0
	v_readlane_b32 s5, v248, 2
	v_readlane_b32 s6, v248, 3
	s_mul_i32 s1, s4, 3
	s_add_i32 s0, s0, s1
	s_mulk_i32 s0, 0x1800
	s_ashr_i32 s1, s0, 31
	s_lshl_b64 s[0:1], s[0:1], 2
	s_add_u32 s0, s5, s0
	s_addc_u32 s1, s6, s1
	v_lshl_or_b32 v0, s42, 8, v218
	v_lshlrev_b32_e32 v0, 2, v0
	global_load_dwordx4 v[130:133], v0, s[0:1] offset:0
	s_add_u32 s8, s94, 0x139d6000
	s_addc_u32 s9, s95, 0
	s_add_u32 s10, s94, 0x1e40000
	s_addc_u32 s11, s95, 0
	s_cmp_eq_u32 s56, 3
	s_cbranch_scc1 .Lepi_w1
	s_mov_b64 s[12:13], s[8:9]
	s_mov_b64 s[14:15], s[10:11]
	s_cmp_lg_u32 s4, 0
	s_cbranch_scc1 .Lepi_bd
	v_readlane_b32 s14, v250, 43
	v_readlane_b32 s15, v250, 44
	s_cmp_lt_i32 s24, 0x1000
	s_cbranch_scc1 .Lepi_bd
	v_readlane_b32 s14, v250, 45
	v_readlane_b32 s15, v250, 46
	s_nop 1
	s_sub_u32 s14, s14, 0x1000000
	s_subb_u32 s15, s15, 0
	s_branch .Lepi_bd
.Lepi_w1:
	s_mov_b64 s[12:13], s[10:11]
	s_mov_b64 s[14:15], s[8:9]
.Lepi_bd:
	s_nop 1
	s_lshl_b32 s16, s24, 12
	s_lshl_b32 s17, s42, 10
	s_add_u32 s16, s16, s17
	s_add_u32 s12, s12, s16
	s_addc_u32 s13, s13, 0
	s_add_u32 s14, s14, s16
	s_addc_u32 s15, s15, 0
	v_lshlrev_b32_e32 v224, 12, v143
	v_lshl_add_u32 v224, v218, 2, v224
	v_add_u32_e32 v225, 0x0, v224
	global_load_dwordx4 v[150:153], v225, s[14:15] offset:0
	v_add_u32_e32 v239, 0x10000, v224
	global_load_dwordx4 v[154:157], v239, s[14:15] offset:0
	v_add_u32_e32 v225, 0x20000, v224
	global_load_dwordx4 v[158:161], v225, s[14:15] offset:0
	v_add_u32_e32 v239, 0x30000, v224
	global_load_dwordx4 v[162:165], v239, s[14:15] offset:0
	v_add_u32_e32 v225, 0x80000, v224
	global_load_dwordx4 v[166:169], v225, s[14:15] offset:0
	v_add_u32_e32 v239, 0x90000, v224
	global_load_dwordx4 v[170:173], v239, s[14:15] offset:0
	v_add_u32_e32 v225, 0xa0000, v224
	global_load_dwordx4 v[174:177], v225, s[14:15] offset:0
	v_add_u32_e32 v239, 0xb0000, v224
	global_load_dwordx4 v[178:181], v239, s[14:15] offset:0
	v_add_u32_e32 v225, 0x0, v224
	global_load_dwordx4 v[182:185], v225, s[14:15] offset:64
	v_add_u32_e32 v239, 0x10000, v224
	global_load_dwordx4 v[186:189], v239, s[14:15] offset:64
	v_add_u32_e32 v225, 0x20000, v224
	global_load_dwordx4 v[190:193], v225, s[14:15] offset:64
	v_add_u32_e32 v239, 0x30000, v224
	global_load_dwordx4 v[194:197], v239, s[14:15] offset:64
	s_waitcnt vmcnt(8)
	v_fma_f32 v150, v126, v130, v150
	v_fma_f32 v151, v127, v131, v151
	v_fma_f32 v152, v128, v132, v152
	v_fma_f32 v153, v129, v133, v153
	v_fma_f32 v154, v118, v130, v154
	v_fma_f32 v155, v119, v131, v155
	v_fma_f32 v156, v120, v132, v156
	v_fma_f32 v157, v121, v133, v157
	v_fma_f32 v158, v110, v130, v158
	v_fma_f32 v159, v111, v131, v159
	v_fma_f32 v160, v112, v132, v160
	v_fma_f32 v161, v113, v133, v161
	v_fma_f32 v162, v102, v130, v162
	v_fma_f32 v163, v103, v131, v163
	v_fma_f32 v164, v104, v132, v164
	v_fma_f32 v165, v105, v133, v165
	v_add_u32_e32 v242, 0x0, v224
	global_store_dwordx4 v242, v[150:153], s[12:13] offset:0
	v_add_u32_e32 v245, 0x10000, v224
	global_store_dwordx4 v245, v[154:157], s[12:13] offset:0
	v_add_u32_e32 v242, 0x20000, v224
	global_store_dwordx4 v242, v[158:161], s[12:13] offset:0
	v_add_u32_e32 v245, 0x30000, v224
	global_store_dwordx4 v245, v[162:165], s[12:13] offset:0
	global_load_dword v227, v0, s[0:1] offset:64
	global_load_dword v230, v0, s[0:1] offset:68
	global_load_dword v233, v0, s[0:1] offset:72
	global_load_dword v236, v0, s[0:1] offset:76
	v_add_u32_e32 v225, 0x80000, v224
	global_load_dwordx4 v[150:153], v225, s[14:15] offset:64
	v_add_u32_e32 v239, 0x90000, v224
	global_load_dwordx4 v[154:157], v239, s[14:15] offset:64
	v_add_u32_e32 v225, 0xa0000, v224
	global_load_dwordx4 v[158:161], v225, s[14:15] offset:64
	v_add_u32_e32 v239, 0xb0000, v224
	global_load_dwordx4 v[162:165], v239, s[14:15] offset:64
	s_waitcnt vmcnt(16)
	v_fma_f32 v166, v94, v130, v166
	v_fma_f32 v167, v95, v131, v167
	v_fma_f32 v168, v96, v132, v168
	v_fma_f32 v169, v97, v133, v169
	v_fma_f32 v170, v86, v130, v170
	v_fma_f32 v171, v87, v131, v171
	v_fma_f32 v172, v88, v132, v172
	v_fma_f32 v173, v89, v133, v173
	v_fma_f32 v174, v78, v130, v174
	v_fma_f32 v175, v79, v131, v175
	v_fma_f32 v176, v80, v132, v176
	v_fma_f32 v177, v81, v133, v177
	v_fma_f32 v178, v70, v130, v178
	v_fma_f32 v179, v71, v131, v179
	v_fma_f32 v180, v72, v132, v180
	v_fma_f32 v181, v73, v133, v181
	v_add_u32_e32 v242, 0x80000, v224
	global_store_dwordx4 v242, v[166:169], s[12:13] offset:0
	v_add_u32_e32 v245, 0x90000, v224
	global_store_dwordx4 v245, v[170:173], s[12:13] offset:0
	v_add_u32_e32 v242, 0xa0000, v224
	global_store_dwordx4 v242, v[174:177], s[12:13] offset:0
	v_add_u32_e32 v245, 0xb0000, v224
	global_store_dwordx4 v245, v[178:181], s[12:13] offset:0
	v_add_u32_e32 v225, 0x0, v224
	global_load_dwordx4 v[166:169], v225, s[14:15] offset:512
	v_add_u32_e32 v239, 0x10000, v224
	global_load_dwordx4 v[170:173], v239, s[14:15] offset:512
	v_add_u32_e32 v225, 0x20000, v224
	global_load_dwordx4 v[174:177], v225, s[14:15] offset:512
	v_add_u32_e32 v239, 0x30000, v224
	global_load_dwordx4 v[178:181], v239, s[14:15] offset:512
	s_waitcnt vmcnt(12)
	v_fma_f32 v182, v122, v227, v182
	v_fma_f32 v183, v123, v230, v183
	v_fma_f32 v184, v124, v233, v184
	v_fma_f32 v185, v125, v236, v185
	v_fma_f32 v186, v114, v227, v186
	v_fma_f32 v187, v115, v230, v187
	v_fma_f32 v188, v116, v233, v188
	v_fma_f32 v189, v117, v236, v189
	v_fma_f32 v190, v106, v227, v190
	v_fma_f32 v191, v107, v230, v191
	v_fma_f32 v192, v108, v233, v192
	v_fma_f32 v193, v109, v236, v193
	v_fma_f32 v194, v98, v227, v194
	v_fma_f32 v195, v99, v230, v195
	v_fma_f32 v196, v100, v233, v196
	v_fma_f32 v197, v101, v236, v197
	v_add_u32_e32 v242, 0x0, v224
	global_store_dwordx4 v242, v[182:185], s[12:13] offset:64
	v_add_u32_e32 v245, 0x10000, v224
	global_store_dwordx4 v245, v[186:189], s[12:13] offset:64
	v_add_u32_e32 v242, 0x20000, v224
	global_store_dwordx4 v242, v[190:193], s[12:13] offset:64
	v_add_u32_e32 v245, 0x30000, v224
	global_store_dwordx4 v245, v[194:197], s[12:13] offset:64
	global_load_dwordx4 v[130:133], v0, s[0:1] offset:512
	v_add_u32_e32 v225, 0x80000, v224
	global_load_dwordx4 v[182:185], v225, s[14:15] offset:512
	v_add_u32_e32 v239, 0x90000, v224
	global_load_dwordx4 v[186:189], v239, s[14:15] offset:512
	v_add_u32_e32 v225, 0xa0000, v224
	global_load_dwordx4 v[190:193], v225, s[14:15] offset:512
	v_add_u32_e32 v239, 0xb0000, v224
	global_load_dwordx4 v[194:197], v239, s[14:15] offset:512
	s_waitcnt vmcnt(17)
	v_fma_f32 v150, v90, v227, v150
	v_fma_f32 v151, v91, v230, v151
	v_fma_f32 v152, v92, v233, v152
	v_fma_f32 v153, v93, v236, v153
	v_fma_f32 v154, v82, v227, v154
	v_fma_f32 v155, v83, v230, v155
	v_fma_f32 v156, v84, v233, v156
	v_fma_f32 v157, v85, v236, v157
	v_fma_f32 v158, v74, v227, v158
	v_fma_f32 v159, v75, v230, v159
	v_fma_f32 v160, v76, v233, v160
	v_fma_f32 v161, v77, v236, v161
	v_fma_f32 v162, v66, v227, v162
	v_fma_f32 v163, v67, v230, v163
	v_fma_f32 v164, v68, v233, v164
	v_fma_f32 v165, v69, v236, v165
	v_add_u32_e32 v242, 0x80000, v224
	global_store_dwordx4 v242, v[150:153], s[12:13] offset:64
	v_add_u32_e32 v245, 0x90000, v224
	global_store_dwordx4 v245, v[154:157], s[12:13] offset:64
	v_add_u32_e32 v242, 0xa0000, v224
	global_store_dwordx4 v242, v[158:161], s[12:13] offset:64
	v_add_u32_e32 v245, 0xb0000, v224
	global_store_dwordx4 v245, v[162:165], s[12:13] offset:64
	v_add_u32_e32 v225, 0x0, v224
	global_load_dwordx4 v[150:153], v225, s[14:15] offset:576
	v_add_u32_e32 v239, 0x10000, v224
	global_load_dwordx4 v[154:157], v239, s[14:15] offset:576
	v_add_u32_e32 v225, 0x20000, v224
	global_load_dwordx4 v[158:161], v225, s[14:15] offset:576
	v_add_u32_e32 v239, 0x30000, v224
	global_load_dwordx4 v[162:165], v239, s[14:15] offset:576
	s_waitcnt vmcnt(12)
	v_fma_f32 v166, v62, v130, v166
	v_fma_f32 v167, v63, v131, v167
	v_fma_f32 v168, v64, v132, v168
	v_fma_f32 v169, v65, v133, v169
	v_fma_f32 v170, v54, v130, v170
	v_fma_f32 v171, v55, v131, v171
	v_fma_f32 v172, v56, v132, v172
	v_fma_f32 v173, v57, v133, v173
	v_fma_f32 v174, v46, v130, v174
	v_fma_f32 v175, v47, v131, v175
	v_fma_f32 v176, v48, v132, v176
	v_fma_f32 v177, v49, v133, v177
	v_fma_f32 v178, v38, v130, v178
	v_fma_f32 v179, v39, v131, v179
	v_fma_f32 v180, v40, v132, v180
	v_fma_f32 v181, v41, v133, v181
	v_add_u32_e32 v242, 0x0, v224
	global_store_dwordx4 v242, v[166:169], s[12:13] offset:512
	v_add_u32_e32 v245, 0x10000, v224
	global_store_dwordx4 v245, v[170:173], s[12:13] offset:512
	v_add_u32_e32 v242, 0x20000, v224
	global_store_dwordx4 v242, v[174:177], s[12:13] offset:512
	v_add_u32_e32 v245, 0x30000, v224
	global_store_dwordx4 v245, v[178:181], s[12:13] offset:512
	global_load_dword v227, v0, s[0:1] offset:576
	global_load_dword v230, v0, s[0:1] offset:580
	global_load_dword v233, v0, s[0:1] offset:584
	global_load_dword v236, v0, s[0:1] offset:588
	v_add_u32_e32 v225, 0x80000, v224
	global_load_dwordx4 v[166:169], v225, s[14:15] offset:576
	v_add_u32_e32 v239, 0x90000, v224
	global_load_dwordx4 v[170:173], v239, s[14:15] offset:576
	v_add_u32_e32 v225, 0xa0000, v224
	global_load_dwordx4 v[174:177], v225, s[14:15] offset:576
	v_add_u32_e32 v239, 0xb0000, v224
	global_load_dwordx4 v[178:181], v239, s[14:15] offset:576
	s_waitcnt vmcnt(20)
	v_fma_f32 v182, v30, v130, v182
	v_fma_f32 v183, v31, v131, v183
	v_fma_f32 v184, v32, v132, v184
	v_fma_f32 v185, v33, v133, v185
	v_fma_f32 v186, v22, v130, v186
	v_fma_f32 v187, v23, v131, v187
	v_fma_f32 v188, v24, v132, v188
	v_fma_f32 v189, v25, v133, v189
	v_fma_f32 v190, v14, v130, v190
	v_fma_f32 v191, v15, v131, v191
	v_fma_f32 v192, v16, v132, v192
	v_fma_f32 v193, v17, v133, v193
	v_fma_f32 v194, v6, v130, v194
	v_fma_f32 v195, v7, v131, v195
	v_fma_f32 v196, v8, v132, v196
	v_fma_f32 v197, v9, v133, v197
	v_add_u32_e32 v242, 0x80000, v224
	global_store_dwordx4 v242, v[182:185], s[12:13] offset:512
	v_add_u32_e32 v245, 0x90000, v224
	global_store_dwordx4 v245, v[186:189], s[12:13] offset:512
	v_add_u32_e32 v242, 0xa0000, v224
	global_store_dwordx4 v242, v[190:193], s[12:13] offset:512
	v_add_u32_e32 v245, 0xb0000, v224
	global_store_dwordx4 v245, v[194:197], s[12:13] offset:512
	s_waitcnt vmcnt(8)
	v_fma_f32 v150, v58, v227, v150
	v_fma_f32 v151, v59, v230, v151
	v_fma_f32 v152, v60, v233, v152
	v_fma_f32 v153, v61, v236, v153
	v_fma_f32 v154, v50, v227, v154
	v_fma_f32 v155, v51, v230, v155
	v_fma_f32 v156, v52, v233, v156
	v_fma_f32 v157, v53, v236, v157
	v_fma_f32 v158, v42, v227, v158
	v_fma_f32 v159, v43, v230, v159
	v_fma_f32 v160, v44, v233, v160
	v_fma_f32 v161, v45, v236, v161
	v_fma_f32 v162, v34, v227, v162
	v_fma_f32 v163, v35, v230, v163
	v_fma_f32 v164, v36, v233, v164
	v_fma_f32 v165, v37, v236, v165
	v_add_u32_e32 v242, 0x0, v224
	global_store_dwordx4 v242, v[150:153], s[12:13] offset:576
	v_add_u32_e32 v245, 0x10000, v224
	global_store_dwordx4 v245, v[154:157], s[12:13] offset:576
	v_add_u32_e32 v242, 0x20000, v224
	global_store_dwordx4 v242, v[158:161], s[12:13] offset:576
	v_add_u32_e32 v245, 0x30000, v224
	global_store_dwordx4 v245, v[162:165], s[12:13] offset:576
	s_waitcnt vmcnt(8)
	v_fma_f32 v166, v26, v227, v166
	v_fma_f32 v167, v27, v230, v167
	v_fma_f32 v168, v28, v233, v168
	v_fma_f32 v169, v29, v236, v169
	v_fma_f32 v170, v18, v227, v170
	v_fma_f32 v171, v19, v230, v171
	v_fma_f32 v172, v20, v233, v172
	v_fma_f32 v173, v21, v236, v173
	v_fma_f32 v174, v10, v227, v174
	v_fma_f32 v175, v11, v230, v175
	v_fma_f32 v176, v12, v233, v176
	v_fma_f32 v177, v13, v236, v177
	v_fma_f32 v178, v2, v227, v178
	v_fma_f32 v179, v3, v230, v179
	v_fma_f32 v180, v4, v233, v180
	v_fma_f32 v181, v5, v236, v181
	v_add_u32_e32 v242, 0x80000, v224
	global_store_dwordx4 v242, v[166:169], s[12:13] offset:576
	v_add_u32_e32 v245, 0x90000, v224
	global_store_dwordx4 v245, v[170:173], s[12:13] offset:576
	v_add_u32_e32 v242, 0xa0000, v224
	global_store_dwordx4 v242, v[174:177], s[12:13] offset:576
	v_add_u32_e32 v245, 0xb0000, v224
	global_store_dwordx4 v245, v[178:181], s[12:13] offset:576
	s_mov_b64 s[0:1], 0
